# resid epilogue: boundary-straddling tiles skip the first gate wait and issue all gate loads in one round trip
# speedup vs baseline: 1.0092x; 1.0018x over previous
.LBB0_896:
	v_readlane_b32 s0, v254, 38
	v_readlane_b32 s1, v254, 39
	s_xor_b64 s[18:19], s[4:5], -1
	s_lshl_b64 s[0:1], s[0:1], 2
	s_add_u32 s4, s24, s0
	s_addc_u32 s5, s25, s1
	v_readlane_b32 s0, v254, 47
	v_readlane_b32 s1, v254, 48
	s_and_b64 s[0:1], s[0:1], exec
	s_movk_i32 s0, 0x5000
	s_cselect_b32 s0, 0x2000, s0
	s_add_u32 s12, s4, s0
	s_addc_u32 s13, s5, 0
	v_ashrrev_i32_e32 v243, 31, v242
	v_lshl_add_u64 v[106:107], v[106:107], 2, s[12:13]
	v_lshl_add_u64 v[106:107], v[242:243], 2, v[106:107]
	flat_load_dwordx4 v[210:213], v[106:107] offset:16
	flat_load_dwordx4 v[214:217], v[106:107]
	flat_load_dwordx4 v[206:209], v[106:107] offset:528
	flat_load_dwordx2 v[244:245], v[106:107] offset:512
	flat_load_dwordx2 v[250:251], v[106:107] offset:520
	v_cndmask_b32_e64 v0, 0, 1, s[18:19]
	s_movk_i32 s0, 0x1fef
	v_cmp_lt_i32_e64 s[4:5], s0, v249
	v_cmp_ne_u32_e64 s[0:1], 1, v0
	s_andn2_b64 vcc, exec, s[18:19]
	s_cbranch_vccz .Lgc_w0
	s_waitcnt vmcnt(0) lgkmcnt(0)
.Lgc_w0:
	v_mov_b64_e32 v[186:187], v[210:211]
	v_mov_b64_e32 v[194:195], v[214:215]
	v_mov_b64_e32 v[188:189], v[212:213]
	v_mov_b64_e32 v[196:197], v[216:217]
	s_cbranch_vccnz .LBB0_898
	s_add_i32 s15, s14, 0xffffe010
	s_lshr_b32 s15, s15, 10
	s_mulk_i32 s15, 0x1800
	s_addk_i32 s15, 0x1800
	v_mov_b32_e32 v0, s15
	v_cndmask_b32_e64 v0, 0, v0, s[4:5]
	v_lshl_add_u64 v[106:107], v[0:1], 2, s[12:13]
	v_lshl_add_u64 v[106:107], v[242:243], 2, v[106:107]
	flat_load_dwordx4 v[194:197], v[106:107]
	flat_load_dwordx4 v[186:189], v[106:107] offset:16

.LBB0_908:
	v_lshl_add_u64 v[130:131], v[130:131], 2, s[12:13]
	v_lshl_add_u64 v[130:131], v[242:243], 2, v[130:131]
	s_and_b64 vcc, exec, s[0:1]
	s_cbranch_vccz .Lgc_ld
	v_mov_b64_e32 v[234:235], v[206:207]
	v_mov_b64_e32 v[236:237], v[208:209]
	v_mov_b64_e32 v[238:239], v[244:245]
	v_mov_b64_e32 v[240:241], v[250:251]
	s_branch .Lgc_ldd
.Lgc_ld:
	flat_load_dwordx4 v[234:237], v[130:131] offset:528
	flat_load_dwordx4 v[238:241], v[130:131] offset:512
.Lgc_ldd:
	s_and_b64 vcc, exec, s[0:1]
	v_mov_b64_e32 v[222:223], v[234:235]
	v_mov_b64_e32 v[226:227], v[238:239]
	v_mov_b64_e32 v[224:225], v[236:237]
	v_mov_b64_e32 v[228:229], v[240:241]
	s_cbranch_vccnz .LBB0_910
	s_add_i32 s4, s14, 0xffffe010
	s_lshr_b32 s4, s4, 10
	s_mulk_i32 s4, 0x1800
	s_addk_i32 s4, 0x1800
	v_mov_b32_e32 v0, s4
	s_movk_i32 s4, 0x1fef
	v_cmp_lt_i32_e32 vcc, s4, v249
	s_nop 1
	v_cndmask_b32_e32 v0, 0, v0, vcc
	v_lshl_add_u64 v[130:131], v[0:1], 2, s[12:13]
	v_lshl_add_u64 v[130:131], v[242:243], 2, v[130:131]
	flat_load_dwordx4 v[226:229], v[130:131] offset:512
	flat_load_dwordx4 v[222:225], v[130:131] offset:528
